# stack + out-projection epilogue hand-written with the residual x loads batched ahead of the math
# baseline (speedup 1.0000x reference)
.LBB0_652:
	s_mov_b32 s68, s84
	s_lshl_b32 s38, s12, 8
	s_mov_b32 s101, 0
	s_cmp_ge_u32 s38, 0x8000
	s_cselect_b32 s98, s18, s16
	s_cselect_b32 s99, s19, s17
	s_cselect_b32 s40, 0x8000, 0
	s_sub_u32 s100, s38, s40
	s_lshl_b64 s[100:101], s[100:101], 12
	s_add_u32 s98, s98, s100
	s_addc_u32 s99, s99, s101
	s_mov_b32 s100, s38
	s_mov_b32 s101, 0
	s_lshl_b64 s[100:101], s[100:101], 11
	s_add_u32 s100, s20, s100
	s_addc_u32 s101, s21, s101
	v_lshl_or_b32 v146, s34, 8, v154
	v_lshlrev_b32_e32 v147, 2, v146
	v_lshlrev_b32_e32 v148, 1, v146
	v_lshl_add_u32 v226, v152, 12, v147
	v_lshl_add_u32 v227, v152, 11, v148
	v_lshl_add_u32 v149, s12, 8, v152
	s_lshl_b32 s39, s34, 4
	s_lshl2_add_u32 s39, s35, s39
	v_lshlrev_b32_e32 v149, 6, v149
	v_add_u32_e32 v228, s39, v149
	global_load_dwordx4 v[162:165], v226, s[98:99]
	global_load_dwordx4 v[166:169], v226, s[98:99] offset:16
	global_load_dwordx4 v[170:173], v226, s[98:99] offset:512
	global_load_dwordx4 v[174:177], v226, s[98:99] offset:528
	v_add_u32_e32 v229, 0x10000, v226
	global_load_dwordx4 v[178:181], v229, s[98:99]
	global_load_dwordx4 v[182:185], v229, s[98:99] offset:16
	global_load_dwordx4 v[186:189], v229, s[98:99] offset:512
	global_load_dwordx4 v[190:193], v229, s[98:99] offset:528
	v_add_u32_e32 v229, 0x20000, v226
	global_load_dwordx4 v[194:197], v229, s[98:99]
	global_load_dwordx4 v[198:201], v229, s[98:99] offset:16
	global_load_dwordx4 v[202:205], v229, s[98:99] offset:512
	global_load_dwordx4 v[206:209], v229, s[98:99] offset:528
	v_add_u32_e32 v229, 0x30000, v226
	global_load_dwordx4 v[210:213], v229, s[98:99]
	global_load_dwordx4 v[214:217], v229, s[98:99] offset:16
	global_load_dwordx4 v[218:221], v229, s[98:99] offset:512
	global_load_dwordx4 v[222:225], v229, s[98:99] offset:528
	s_waitcnt vmcnt(12)
	v_pk_add_f32 v[124:125], v[124:125], v[162:163]
	v_pk_add_f32 v[126:127], v[126:127], v[164:165]
	v_pk_add_f32 v[120:121], v[120:121], v[166:167]
	v_pk_add_f32 v[122:123], v[122:123], v[168:169]
	v_pk_add_f32 v[116:117], v[116:117], v[170:171]
	v_pk_add_f32 v[118:119], v[118:119], v[172:173]
	v_pk_add_f32 v[112:113], v[112:113], v[174:175]
	v_pk_add_f32 v[114:115], v[114:115], v[176:177]
	v_mul_f32_e32 v230, v127, v127
	v_mul_f32_e32 v231, v125, v125
	v_mul_f32_e32 v232, v121, v121
	v_mul_f32_e32 v233, v123, v123
	v_fmac_f32_e32 v230, v126, v126
	v_fmac_f32_e32 v231, v124, v124
	v_fmac_f32_e32 v232, v120, v120
	v_fmac_f32_e32 v233, v122, v122
	v_add_f32_e32 v234, v231, v230
	v_add_f32_e32 v234, v234, v232
	v_add_f32_e32 v234, v233, v234
	v_mul_f32_e32 v230, v119, v119
	v_mul_f32_e32 v231, v117, v117
	v_mul_f32_e32 v232, v113, v113
	v_mul_f32_e32 v233, v115, v115
	v_fmac_f32_e32 v230, v118, v118
	v_fmac_f32_e32 v231, v116, v116
	v_fmac_f32_e32 v232, v112, v112
	v_fmac_f32_e32 v233, v114, v114
	v_add_f32_e32 v235, v231, v230
	v_add_f32_e32 v235, v235, v232
	v_add_f32_e32 v235, v233, v235
	v_add_f32_e32 v237, v234, v235
	v_mov_b32_e32 v236, v237
	v_cvt_pk_bf16_f32 v124, v124, v125
	v_cvt_pk_bf16_f32 v125, v126, v127
	v_cvt_pk_bf16_f32 v126, v120, v121
	v_cvt_pk_bf16_f32 v127, v122, v123
	v_permlane16_swap_b32_e32 v237, v236
	v_cvt_pk_bf16_f32 v116, v116, v117
	v_cvt_pk_bf16_f32 v117, v118, v119
	v_add_f32_e32 v237, v237, v236
	v_cvt_pk_bf16_f32 v118, v112, v113
	v_cvt_pk_bf16_f32 v119, v114, v115
	v_mov_b32_e32 v236, v237
	s_nop 0
	global_store_dwordx4 v227, v[124:127], s[100:101]
	global_store_dwordx4 v227, v[116:119], s[100:101] offset:256
	v_permlane32_swap_b32_e32 v237, v236
	v_add_u32_e32 v229, 0x80000, v226
	global_load_dwordx4 v[120:123], v229, s[98:99]
	global_load_dwordx4 v[112:115], v229, s[98:99] offset:16
	global_load_dwordx4 v[124:127], v229, s[98:99] offset:512
	global_load_dwordx4 v[116:119], v229, s[98:99] offset:528
	v_add_f32_e32 v237, v237, v236
	s_waitcnt vmcnt(14)
	v_pk_add_f32 v[108:109], v[108:109], v[178:179]
	v_pk_add_f32 v[110:111], v[110:111], v[180:181]
	v_pk_add_f32 v[104:105], v[104:105], v[182:183]
	v_pk_add_f32 v[106:107], v[106:107], v[184:185]
	v_pk_add_f32 v[100:101], v[100:101], v[186:187]
	v_pk_add_f32 v[102:103], v[102:103], v[188:189]
	v_pk_add_f32 v[96:97], v[96:97], v[190:191]
	v_pk_add_f32 v[98:99], v[98:99], v[192:193]
	v_mul_f32_e32 v230, v111, v111
	v_mul_f32_e32 v231, v109, v109
	v_mul_f32_e32 v232, v105, v105
	v_mul_f32_e32 v233, v107, v107
	v_fmac_f32_e32 v230, v110, v110
	v_fmac_f32_e32 v231, v108, v108
	v_fmac_f32_e32 v232, v104, v104
	v_fmac_f32_e32 v233, v106, v106
	v_add_f32_e32 v234, v231, v230
	v_add_f32_e32 v234, v234, v232
	v_add_f32_e32 v234, v233, v234
	v_mul_f32_e32 v230, v103, v103
	v_mul_f32_e32 v231, v101, v101
	v_mul_f32_e32 v232, v97, v97
	v_mul_f32_e32 v233, v99, v99
	v_fmac_f32_e32 v230, v102, v102
	v_fmac_f32_e32 v231, v100, v100
	v_fmac_f32_e32 v232, v96, v96
	v_fmac_f32_e32 v233, v98, v98
	v_add_f32_e32 v235, v231, v230
	v_add_f32_e32 v235, v235, v232
	v_add_f32_e32 v235, v233, v235
	v_add_f32_e32 v238, v234, v235
	v_mov_b32_e32 v236, v238
	v_cvt_pk_bf16_f32 v108, v108, v109
	v_cvt_pk_bf16_f32 v109, v110, v111
	v_cvt_pk_bf16_f32 v110, v104, v105
	v_cvt_pk_bf16_f32 v111, v106, v107
	v_permlane16_swap_b32_e32 v238, v236
	v_cvt_pk_bf16_f32 v100, v100, v101
	v_cvt_pk_bf16_f32 v101, v102, v103
	v_add_f32_e32 v238, v238, v236
	v_cvt_pk_bf16_f32 v102, v96, v97
	v_cvt_pk_bf16_f32 v103, v98, v99
	v_mov_b32_e32 v236, v238
	v_add_u32_e32 v229, 0x8000, v227
	global_store_dwordx4 v229, v[108:111], s[100:101]
	global_store_dwordx4 v229, v[100:103], s[100:101] offset:256
	v_permlane32_swap_b32_e32 v238, v236
	v_add_u32_e32 v229, 0x90000, v226
	global_load_dwordx4 v[104:107], v229, s[98:99]
	global_load_dwordx4 v[96:99], v229, s[98:99] offset:16
	global_load_dwordx4 v[108:111], v229, s[98:99] offset:512
	global_load_dwordx4 v[100:103], v229, s[98:99] offset:528
	v_add_f32_e32 v238, v238, v236
	s_waitcnt vmcnt(16)
	v_pk_add_f32 v[92:93], v[92:93], v[194:195]
	v_pk_add_f32 v[94:95], v[94:95], v[196:197]
	v_pk_add_f32 v[88:89], v[88:89], v[198:199]
	v_pk_add_f32 v[90:91], v[90:91], v[200:201]
	v_pk_add_f32 v[84:85], v[84:85], v[202:203]
	v_pk_add_f32 v[86:87], v[86:87], v[204:205]
	v_pk_add_f32 v[80:81], v[80:81], v[206:207]
	v_pk_add_f32 v[82:83], v[82:83], v[208:209]
	v_mul_f32_e32 v230, v95, v95
	v_mul_f32_e32 v231, v93, v93
	v_mul_f32_e32 v232, v89, v89
	v_mul_f32_e32 v233, v91, v91
	v_fmac_f32_e32 v230, v94, v94
	v_fmac_f32_e32 v231, v92, v92
	v_fmac_f32_e32 v232, v88, v88
	v_fmac_f32_e32 v233, v90, v90
	v_add_f32_e32 v234, v231, v230
	v_add_f32_e32 v234, v234, v232
	v_add_f32_e32 v234, v233, v234
	v_mul_f32_e32 v230, v87, v87
	v_mul_f32_e32 v231, v85, v85
	v_mul_f32_e32 v232, v81, v81
	v_mul_f32_e32 v233, v83, v83
	v_fmac_f32_e32 v230, v86, v86
	v_fmac_f32_e32 v231, v84, v84
	v_fmac_f32_e32 v232, v80, v80
	v_fmac_f32_e32 v233, v82, v82
	v_add_f32_e32 v235, v231, v230
	v_add_f32_e32 v235, v235, v232
	v_add_f32_e32 v235, v233, v235
	v_add_f32_e32 v239, v234, v235
	v_mov_b32_e32 v236, v239
	v_cvt_pk_bf16_f32 v92, v92, v93
	v_cvt_pk_bf16_f32 v93, v94, v95
	v_cvt_pk_bf16_f32 v94, v88, v89
	v_cvt_pk_bf16_f32 v95, v90, v91
	v_permlane16_swap_b32_e32 v239, v236
	v_cvt_pk_bf16_f32 v84, v84, v85
	v_cvt_pk_bf16_f32 v85, v86, v87
	v_add_f32_e32 v239, v239, v236
	v_cvt_pk_bf16_f32 v86, v80, v81
	v_cvt_pk_bf16_f32 v87, v82, v83
	v_mov_b32_e32 v236, v239
	v_add_u32_e32 v229, 0x10000, v227
	global_store_dwordx4 v229, v[92:95], s[100:101]
	global_store_dwordx4 v229, v[84:87], s[100:101] offset:256
	v_permlane32_swap_b32_e32 v239, v236
	v_add_u32_e32 v229, 0xa0000, v226
	global_load_dwordx4 v[88:91], v229, s[98:99]
	global_load_dwordx4 v[80:83], v229, s[98:99] offset:16
	global_load_dwordx4 v[92:95], v229, s[98:99] offset:512
	global_load_dwordx4 v[84:87], v229, s[98:99] offset:528
	v_add_f32_e32 v239, v239, v236
	s_waitcnt vmcnt(18)
	v_pk_add_f32 v[76:77], v[76:77], v[210:211]
	v_pk_add_f32 v[78:79], v[78:79], v[212:213]
	v_pk_add_f32 v[72:73], v[72:73], v[214:215]
	v_pk_add_f32 v[74:75], v[74:75], v[216:217]
	v_pk_add_f32 v[68:69], v[68:69], v[218:219]
	v_pk_add_f32 v[70:71], v[70:71], v[220:221]
	v_pk_add_f32 v[64:65], v[64:65], v[222:223]
	v_pk_add_f32 v[66:67], v[66:67], v[224:225]
	v_mul_f32_e32 v230, v79, v79
	v_mul_f32_e32 v231, v77, v77
	v_mul_f32_e32 v232, v73, v73
	v_mul_f32_e32 v233, v75, v75
	v_fmac_f32_e32 v230, v78, v78
	v_fmac_f32_e32 v231, v76, v76
	v_fmac_f32_e32 v232, v72, v72
	v_fmac_f32_e32 v233, v74, v74
	v_add_f32_e32 v234, v231, v230
	v_add_f32_e32 v234, v234, v232
	v_add_f32_e32 v234, v233, v234
	v_mul_f32_e32 v230, v71, v71
	v_mul_f32_e32 v231, v69, v69
	v_mul_f32_e32 v232, v65, v65
	v_mul_f32_e32 v233, v67, v67
	v_fmac_f32_e32 v230, v70, v70
	v_fmac_f32_e32 v231, v68, v68
	v_fmac_f32_e32 v232, v64, v64
	v_fmac_f32_e32 v233, v66, v66
	v_add_f32_e32 v235, v231, v230
	v_add_f32_e32 v235, v235, v232
	v_add_f32_e32 v235, v233, v235
	v_add_f32_e32 v240, v234, v235
	v_mov_b32_e32 v236, v240
	v_cvt_pk_bf16_f32 v76, v76, v77
	v_cvt_pk_bf16_f32 v77, v78, v79
	v_cvt_pk_bf16_f32 v78, v72, v73
	v_cvt_pk_bf16_f32 v79, v74, v75
	v_permlane16_swap_b32_e32 v240, v236
	v_cvt_pk_bf16_f32 v68, v68, v69
	v_cvt_pk_bf16_f32 v69, v70, v71
	v_add_f32_e32 v240, v240, v236
	v_cvt_pk_bf16_f32 v70, v64, v65
	v_cvt_pk_bf16_f32 v71, v66, v67
	v_mov_b32_e32 v236, v240
	v_add_u32_e32 v229, 0x18000, v227
	global_store_dwordx4 v229, v[76:79], s[100:101]
	global_store_dwordx4 v229, v[68:71], s[100:101] offset:256
	v_permlane32_swap_b32_e32 v240, v236
	v_add_u32_e32 v229, 0xb0000, v226
	global_load_dwordx4 v[72:75], v229, s[98:99]
	global_load_dwordx4 v[64:67], v229, s[98:99] offset:16
	global_load_dwordx4 v[76:79], v229, s[98:99] offset:512
	global_load_dwordx4 v[68:71], v229, s[98:99] offset:528
	v_add_f32_e32 v240, v240, v236
	s_waitcnt vmcnt(18)
	v_pk_add_f32 v[60:61], v[60:61], v[120:121]
	v_pk_add_f32 v[62:63], v[62:63], v[122:123]
	v_pk_add_f32 v[56:57], v[56:57], v[112:113]
	v_pk_add_f32 v[58:59], v[58:59], v[114:115]
	v_pk_add_f32 v[52:53], v[52:53], v[124:125]
	v_pk_add_f32 v[54:55], v[54:55], v[126:127]
	v_pk_add_f32 v[48:49], v[48:49], v[116:117]
	v_pk_add_f32 v[50:51], v[50:51], v[118:119]
	v_mul_f32_e32 v230, v63, v63
	v_mul_f32_e32 v231, v61, v61
	v_mul_f32_e32 v232, v57, v57
	v_mul_f32_e32 v233, v59, v59
	v_fmac_f32_e32 v230, v62, v62
	v_fmac_f32_e32 v231, v60, v60
	v_fmac_f32_e32 v232, v56, v56
	v_fmac_f32_e32 v233, v58, v58
	v_add_f32_e32 v234, v231, v230
	v_add_f32_e32 v234, v234, v232
	v_add_f32_e32 v234, v233, v234
	v_mul_f32_e32 v230, v55, v55
	v_mul_f32_e32 v231, v53, v53
	v_mul_f32_e32 v232, v49, v49
	v_mul_f32_e32 v233, v51, v51
	v_fmac_f32_e32 v230, v54, v54
	v_fmac_f32_e32 v231, v52, v52
	v_fmac_f32_e32 v232, v48, v48
	v_fmac_f32_e32 v233, v50, v50
	v_add_f32_e32 v235, v231, v230
	v_add_f32_e32 v235, v235, v232
	v_add_f32_e32 v235, v233, v235
	v_add_f32_e32 v241, v234, v235
	v_mov_b32_e32 v236, v241
	v_cvt_pk_bf16_f32 v60, v60, v61
	v_cvt_pk_bf16_f32 v61, v62, v63
	v_cvt_pk_bf16_f32 v62, v56, v57
	v_cvt_pk_bf16_f32 v63, v58, v59
	v_permlane16_swap_b32_e32 v241, v236
	v_cvt_pk_bf16_f32 v52, v52, v53
	v_cvt_pk_bf16_f32 v53, v54, v55
	v_add_f32_e32 v241, v241, v236
	v_cvt_pk_bf16_f32 v54, v48, v49
	v_cvt_pk_bf16_f32 v55, v50, v51
	v_mov_b32_e32 v236, v241
	v_add_u32_e32 v229, 0x40000, v227
	global_store_dwordx4 v229, v[60:63], s[100:101]
	global_store_dwordx4 v229, v[52:55], s[100:101] offset:256
	v_permlane32_swap_b32_e32 v241, v236
	s_nop 0
	v_add_f32_e32 v241, v241, v236
	s_waitcnt vmcnt(14)
	v_pk_add_f32 v[44:45], v[44:45], v[104:105]
	v_pk_add_f32 v[46:47], v[46:47], v[106:107]
	v_pk_add_f32 v[40:41], v[40:41], v[96:97]
	v_pk_add_f32 v[42:43], v[42:43], v[98:99]
	v_pk_add_f32 v[36:37], v[36:37], v[108:109]
	v_pk_add_f32 v[38:39], v[38:39], v[110:111]
	v_pk_add_f32 v[32:33], v[32:33], v[100:101]
	v_pk_add_f32 v[34:35], v[34:35], v[102:103]
	v_mul_f32_e32 v230, v47, v47
	v_mul_f32_e32 v231, v45, v45
	v_mul_f32_e32 v232, v41, v41
	v_mul_f32_e32 v233, v43, v43
	v_fmac_f32_e32 v230, v46, v46
	v_fmac_f32_e32 v231, v44, v44
	v_fmac_f32_e32 v232, v40, v40
	v_fmac_f32_e32 v233, v42, v42
	v_add_f32_e32 v234, v231, v230
	v_add_f32_e32 v234, v234, v232
	v_add_f32_e32 v234, v233, v234
	v_mul_f32_e32 v230, v39, v39
	v_mul_f32_e32 v231, v37, v37
	v_mul_f32_e32 v232, v33, v33
	v_mul_f32_e32 v233, v35, v35
	v_fmac_f32_e32 v230, v38, v38
	v_fmac_f32_e32 v231, v36, v36
	v_fmac_f32_e32 v232, v32, v32
	v_fmac_f32_e32 v233, v34, v34
	v_add_f32_e32 v235, v231, v230
	v_add_f32_e32 v235, v235, v232
	v_add_f32_e32 v235, v233, v235
	v_add_f32_e32 v242, v234, v235
	v_mov_b32_e32 v236, v242
	v_cvt_pk_bf16_f32 v44, v44, v45
	v_cvt_pk_bf16_f32 v45, v46, v47
	v_cvt_pk_bf16_f32 v46, v40, v41
	v_cvt_pk_bf16_f32 v47, v42, v43
	v_permlane16_swap_b32_e32 v242, v236
	v_cvt_pk_bf16_f32 v36, v36, v37
	v_cvt_pk_bf16_f32 v37, v38, v39
	v_add_f32_e32 v242, v242, v236
	v_cvt_pk_bf16_f32 v38, v32, v33
	v_cvt_pk_bf16_f32 v39, v34, v35
	v_mov_b32_e32 v236, v242
	v_add_u32_e32 v229, 0x48000, v227
	global_store_dwordx4 v229, v[44:47], s[100:101]
	global_store_dwordx4 v229, v[36:39], s[100:101] offset:256
	v_permlane32_swap_b32_e32 v242, v236
	s_nop 0
	v_add_f32_e32 v242, v242, v236
	s_waitcnt vmcnt(10)
	v_pk_add_f32 v[28:29], v[28:29], v[88:89]
	v_pk_add_f32 v[30:31], v[30:31], v[90:91]
	v_pk_add_f32 v[24:25], v[24:25], v[80:81]
	v_pk_add_f32 v[26:27], v[26:27], v[82:83]
	v_pk_add_f32 v[20:21], v[20:21], v[92:93]
	v_pk_add_f32 v[22:23], v[22:23], v[94:95]
	v_pk_add_f32 v[16:17], v[16:17], v[84:85]
	v_pk_add_f32 v[18:19], v[18:19], v[86:87]
	v_mul_f32_e32 v230, v31, v31
	v_mul_f32_e32 v231, v29, v29
	v_mul_f32_e32 v232, v25, v25
	v_mul_f32_e32 v233, v27, v27
	v_fmac_f32_e32 v230, v30, v30
	v_fmac_f32_e32 v231, v28, v28
	v_fmac_f32_e32 v232, v24, v24
	v_fmac_f32_e32 v233, v26, v26
	v_add_f32_e32 v234, v231, v230
	v_add_f32_e32 v234, v234, v232
	v_add_f32_e32 v234, v233, v234
	v_mul_f32_e32 v230, v23, v23
	v_mul_f32_e32 v231, v21, v21
	v_mul_f32_e32 v232, v17, v17
	v_mul_f32_e32 v233, v19, v19
	v_fmac_f32_e32 v230, v22, v22
	v_fmac_f32_e32 v231, v20, v20
	v_fmac_f32_e32 v232, v16, v16
	v_fmac_f32_e32 v233, v18, v18
	v_add_f32_e32 v235, v231, v230
	v_add_f32_e32 v235, v235, v232
	v_add_f32_e32 v235, v233, v235
	v_add_f32_e32 v243, v234, v235
	v_mov_b32_e32 v236, v243
	v_cvt_pk_bf16_f32 v28, v28, v29
	v_cvt_pk_bf16_f32 v29, v30, v31
	v_cvt_pk_bf16_f32 v30, v24, v25
	v_cvt_pk_bf16_f32 v31, v26, v27
	v_permlane16_swap_b32_e32 v243, v236
	v_cvt_pk_bf16_f32 v20, v20, v21
	v_cvt_pk_bf16_f32 v21, v22, v23
	v_add_f32_e32 v243, v243, v236
	v_cvt_pk_bf16_f32 v22, v16, v17
	v_cvt_pk_bf16_f32 v23, v18, v19
	v_mov_b32_e32 v236, v243
	v_add_u32_e32 v229, 0x50000, v227
	global_store_dwordx4 v229, v[28:31], s[100:101]
	global_store_dwordx4 v229, v[20:23], s[100:101] offset:256
	v_permlane32_swap_b32_e32 v243, v236
	s_nop 0
	v_add_f32_e32 v243, v243, v236
	s_waitcnt vmcnt(6)
	v_pk_add_f32 v[12:13], v[12:13], v[72:73]
	v_pk_add_f32 v[14:15], v[14:15], v[74:75]
	v_pk_add_f32 v[8:9], v[8:9], v[64:65]
	v_pk_add_f32 v[10:11], v[10:11], v[66:67]
	v_pk_add_f32 v[4:5], v[4:5], v[76:77]
	v_pk_add_f32 v[6:7], v[6:7], v[78:79]
	v_pk_add_f32 v[0:1], v[0:1], v[68:69]
	v_pk_add_f32 v[2:3], v[2:3], v[70:71]
	v_mul_f32_e32 v230, v15, v15
	v_mul_f32_e32 v231, v13, v13
	v_mul_f32_e32 v232, v9, v9
	v_mul_f32_e32 v233, v11, v11
	v_fmac_f32_e32 v230, v14, v14
	v_fmac_f32_e32 v231, v12, v12
	v_fmac_f32_e32 v232, v8, v8
	v_fmac_f32_e32 v233, v10, v10
	v_add_f32_e32 v234, v231, v230
	v_add_f32_e32 v234, v234, v232
	v_add_f32_e32 v234, v233, v234
	v_mul_f32_e32 v230, v7, v7
	v_mul_f32_e32 v231, v5, v5
	v_mul_f32_e32 v232, v1, v1
	v_mul_f32_e32 v233, v3, v3
	v_fmac_f32_e32 v230, v6, v6
	v_fmac_f32_e32 v231, v4, v4
	v_fmac_f32_e32 v232, v0, v0
	v_fmac_f32_e32 v233, v2, v2
	v_add_f32_e32 v235, v231, v230
	v_add_f32_e32 v235, v235, v232
	v_add_f32_e32 v235, v233, v235
	v_add_f32_e32 v244, v234, v235
	v_mov_b32_e32 v236, v244
	v_cvt_pk_bf16_f32 v12, v12, v13
	v_cvt_pk_bf16_f32 v13, v14, v15
	v_cvt_pk_bf16_f32 v14, v8, v9
	v_cvt_pk_bf16_f32 v15, v10, v11
	v_permlane16_swap_b32_e32 v244, v236
	v_cvt_pk_bf16_f32 v4, v4, v5
	v_cvt_pk_bf16_f32 v5, v6, v7
	v_add_f32_e32 v244, v244, v236
	v_cvt_pk_bf16_f32 v6, v0, v1
	v_cvt_pk_bf16_f32 v7, v2, v3
	v_mov_b32_e32 v236, v244
	v_add_u32_e32 v229, 0x58000, v227
	global_store_dwordx4 v229, v[12:15], s[100:101]
	global_store_dwordx4 v229, v[4:7], s[100:101] offset:256
	v_permlane32_swap_b32_e32 v244, v236
	s_nop 0
	v_add_f32_e32 v244, v244, v236
	v_add_u32_e32 v229, 0x2000, v228
	s_and_saveexec_b64 s[40:41], s[2:3]
	global_store_dword v228, v237, s[8:9]
	global_store_dword v228, v238, s[8:9] offset:1024
	global_store_dword v228, v239, s[8:9] offset:2048
	global_store_dword v228, v240, s[8:9] offset:3072
	global_store_dword v229, v241, s[8:9]
	global_store_dword v229, v242, s[8:9] offset:1024
	global_store_dword v229, v243, s[8:9] offset:2048
	global_store_dword v229, v244, s[8:9] offset:3072
	s_or_b64 exec, exec, s[40:41]
	s_andn2_b64 vcc, exec, s[4:5]
	s_mov_b64 s[4:5], -1
	s_cbranch_vccnz .LBB0_645
	s_andn2_b64 vcc, exec, s[22:23]
	s_cbranch_vccnz .LBB0_644
	s_barrier
	s_branch .LBB0_644
